# c12 + HGRN next-chunk row loads addressed by one scalar row pointer (s_add/s_addc per token) plus three lane-offset VGPRs instead of 64-bit per-lane address arithmetic per load
# speedup vs baseline: 1.0083x; 1.0083x over previous
.Lhp_issue:
	s_lshl_b32 s52, s48, 6
	s_sub_i32 s53, s46, s52
	s_and_b64 s[50:51], vcc, exec
	s_cselect_b32 s50, s52, s53
	v_add_u32_e32 v32, s50, v74
	v_mad_i64_i32 v[32:33], s[50:51], v32, s39, v[60:61]
	v_and_b32_e32 v34, 63, v188
	v_lshl_add_u64 v[32:33], v[32:33], 0, v[44:45]
	v_lshlrev_b32_e32 v34, 1, v34
	v_add_u32_e32 v36, 0x800, v66
	v_readfirstlane_b32 s52, v32
	v_readfirstlane_b32 s53, v33
	v_add_u32_e32 v35, 0x1800, v34
	v_add_u32_e32 v36, v36, v34
	s_nop 2
	global_load_ushort v75, v34, s[52:53]
	global_load_ushort v52, v36, s[52:53]
	global_load_ushort v76, v35, s[52:53]
	s_add_u32 s52, s52, s36
	s_addc_u32 s53, s53, s37
	global_load_ushort v77, v34, s[52:53]
	global_load_ushort v47, v36, s[52:53]
	global_load_ushort v78, v35, s[52:53]
	s_add_u32 s52, s52, s36
	s_addc_u32 s53, s53, s37
	global_load_ushort v79, v34, s[52:53]
	global_load_ushort v54, v36, s[52:53]
	global_load_ushort v80, v35, s[52:53]
	s_add_u32 s52, s52, s36
	s_addc_u32 s53, s53, s37
	global_load_ushort v81, v34, s[52:53]
	global_load_ushort v49, v36, s[52:53]
	global_load_ushort v82, v35, s[52:53]
	s_add_u32 s52, s52, s36
	s_addc_u32 s53, s53, s37
	global_load_ushort v83, v34, s[52:53]
	global_load_ushort v56, v36, s[52:53]
	global_load_ushort v84, v35, s[52:53]
	s_add_u32 s52, s52, s36
	s_addc_u32 s53, s53, s37
	global_load_ushort v85, v34, s[52:53]
	global_load_ushort v53, v36, s[52:53]
	global_load_ushort v86, v35, s[52:53]
	s_add_u32 s52, s52, s36
	s_addc_u32 s53, s53, s37
	global_load_ushort v87, v34, s[52:53]
	global_load_ushort v58, v36, s[52:53]
	global_load_ushort v89, v35, s[52:53]
	s_add_u32 s52, s52, s36
	s_addc_u32 s53, s53, s37
	global_load_ushort v93, v34, s[52:53]
	global_load_ushort v55, v36, s[52:53]
	global_load_ushort v94, v35, s[52:53]
	s_add_u32 s52, s52, s36
	s_addc_u32 s53, s53, s37
	global_load_ushort v95, v34, s[52:53]
	global_load_ushort v64, v36, s[52:53]
	global_load_ushort v97, v35, s[52:53]
	s_add_u32 s52, s52, s36
	s_addc_u32 s53, s53, s37
	global_load_ushort v103, v34, s[52:53]
	global_load_ushort v57, v36, s[52:53]
	global_load_ushort v105, v35, s[52:53]
	s_add_u32 s52, s52, s36
	s_addc_u32 s53, s53, s37
	global_load_ushort v106, v34, s[52:53]
	global_load_ushort v68, v36, s[52:53]
	global_load_ushort v107, v35, s[52:53]
	s_add_u32 s52, s52, s36
	s_addc_u32 s53, s53, s37
	global_load_ushort v108, v34, s[52:53]
	global_load_ushort v59, v36, s[52:53]
	global_load_ushort v109, v35, s[52:53]
	s_add_u32 s52, s52, s36
	s_addc_u32 s53, s53, s37
	global_load_ushort v110, v34, s[52:53]
	global_load_ushort v70, v36, s[52:53]
	global_load_ushort v111, v35, s[52:53]
	s_add_u32 s52, s52, s36
	s_addc_u32 s53, s53, s37
	global_load_ushort v112, v34, s[52:53]
	global_load_ushort v65, v36, s[52:53]
	global_load_ushort v113, v35, s[52:53]
	s_add_u32 s52, s52, s36
	s_addc_u32 s53, s53, s37
	global_load_ushort v114, v34, s[52:53]
	global_load_ushort v72, v36, s[52:53]
	global_load_ushort v115, v35, s[52:53]
	s_add_u32 s52, s52, s36
	s_addc_u32 s53, s53, s37
	global_load_ushort v116, v34, s[52:53]
	global_load_ushort v51, v35, s[52:53]
	global_load_ushort v67, v36, s[52:53]
	s_cmp_eq_u32 s101, 1
	s_cbranch_scc1 .Lhp_bar
